# mid-block s_setprio 0/1 pairs removed from GEMM MFMA blocks, on top of v20
# speedup vs baseline: 1.0064x; 1.0007x over previous
.LBB0_224:
	ds_read_b128 v[130:133], v208
	ds_read_b128 v[134:137], v208 offset:1024
	ds_read_b128 v[138:141], v208 offset:2048
	ds_read_b128 v[142:145], v208 offset:3072
	ds_read_b128 v[146:149], v209
	ds_read_b128 v[150:153], v209 offset:1024
	ds_read_b128 v[154:157], v209 offset:2048
	ds_read_b128 v[158:161], v209 offset:3072
	s_add_u32 s52, s50, 0xfff00080
	s_addc_u32 s53, s51, -1
	s_cmp_eq_u32 s89, 60
	s_cselect_b32 s55, s43, s53
	s_cselect_b32 s54, s85, s52
	s_cselect_b32 s53, s41, s88
	s_cselect_b32 s52, s86, s87
	v_lshl_add_u64 v[204:205], s[50:51], 0, v[192:193]
	s_add_i32 m0, s56, 0xc000
	ds_read_b128 v[162:165], v210
	ds_read_b128 v[166:169], v210 offset:1024
	ds_read_b128 v[170:173], v210 offset:2048
	ds_read_b128 v[174:177], v210 offset:3072
	ds_read_b128 v[200:203], v210 offset:4096
	ds_read_b128 v[212:215], v210 offset:5120
	ds_read_b128 v[216:219], v210 offset:6144
	ds_read_b128 v[224:227], v210 offset:7168
	global_load_lds_dwordx4 v[204:205], off
	v_lshl_add_u64 v[204:205], s[50:51], 0, v[194:195]
	s_add_i32 m0, s56, 0xe000
	s_nop 0
	global_load_lds_dwordx4 v[204:205], off
	s_waitcnt vmcnt(8)
	s_waitcnt lgkmcnt(0)
	s_setprio 1
	s_barrier
	v_mfma_f32_16x16x32_bf16 v[126:129], v[130:133], v[162:165], v[126:129]
	v_mfma_f32_16x16x32_bf16 v[122:125], v[138:141], v[162:165], v[122:125]
	v_mfma_f32_16x16x32_bf16 v[110:113], v[130:133], v[170:173], v[110:113]
	v_mfma_f32_16x16x32_bf16 v[106:109], v[138:141], v[170:173], v[106:109]
	v_mfma_f32_16x16x32_bf16 v[94:97], v[130:133], v[200:203], v[94:97]
	v_mfma_f32_16x16x32_bf16 v[90:93], v[138:141], v[200:203], v[90:93]
	v_mfma_f32_16x16x32_bf16 v[78:81], v[130:133], v[216:219], v[78:81]
	v_mfma_f32_16x16x32_bf16 v[74:77], v[138:141], v[216:219], v[74:77]
	v_mfma_f32_16x16x32_bf16 v[126:129], v[134:137], v[166:169], v[126:129]
	v_mfma_f32_16x16x32_bf16 v[122:125], v[142:145], v[166:169], v[122:125]
	v_mfma_f32_16x16x32_bf16 v[110:113], v[134:137], v[174:177], v[110:113]
	v_mfma_f32_16x16x32_bf16 v[106:109], v[142:145], v[174:177], v[106:109]
	v_mfma_f32_16x16x32_bf16 v[94:97], v[134:137], v[212:215], v[94:97]
	v_mfma_f32_16x16x32_bf16 v[90:93], v[142:145], v[212:215], v[90:93]
	v_mfma_f32_16x16x32_bf16 v[78:81], v[134:137], v[224:227], v[78:81]
	v_mfma_f32_16x16x32_bf16 v[74:77], v[142:145], v[224:227], v[74:77]
	v_mfma_f32_16x16x32_bf16 v[118:121], v[146:149], v[162:165], v[118:121]
	v_mfma_f32_16x16x32_bf16 v[114:117], v[154:157], v[162:165], v[114:117]
	v_mfma_f32_16x16x32_bf16 v[102:105], v[146:149], v[170:173], v[102:105]
	v_mfma_f32_16x16x32_bf16 v[98:101], v[154:157], v[170:173], v[98:101]
	v_mfma_f32_16x16x32_bf16 v[86:89], v[146:149], v[200:203], v[86:89]
	v_mfma_f32_16x16x32_bf16 v[82:85], v[154:157], v[200:203], v[82:85]
	v_mfma_f32_16x16x32_bf16 v[70:73], v[146:149], v[216:219], v[70:73]
	v_mfma_f32_16x16x32_bf16 v[66:69], v[154:157], v[216:219], v[66:69]
	v_mfma_f32_16x16x32_bf16 v[118:121], v[150:153], v[166:169], v[118:121]
	v_mfma_f32_16x16x32_bf16 v[114:117], v[158:161], v[166:169], v[114:117]
	v_mfma_f32_16x16x32_bf16 v[102:105], v[150:153], v[174:177], v[102:105]
	v_mfma_f32_16x16x32_bf16 v[98:101], v[158:161], v[174:177], v[98:101]
	v_mfma_f32_16x16x32_bf16 v[86:89], v[150:153], v[212:215], v[86:89]
	v_mfma_f32_16x16x32_bf16 v[82:85], v[158:161], v[212:215], v[82:85]
	v_mfma_f32_16x16x32_bf16 v[70:73], v[150:153], v[224:227], v[70:73]
	v_mfma_f32_16x16x32_bf16 v[66:69], v[158:161], v[224:227], v[66:69]
	s_barrier
	s_setprio 0
	s_add_i32 s90, s65, s31
	v_lshl_add_u64 v[204:205], s[52:53], 0, v[182:183]
	s_mov_b32 m0, s90
	ds_read_b128 v[162:165], v210 offset:16384
	ds_read_b128 v[166:169], v210 offset:17408
	ds_read_b128 v[170:173], v210 offset:18432
	ds_read_b128 v[174:177], v210 offset:19456
	ds_read_b128 v[200:203], v210 offset:20480
	ds_read_b128 v[212:215], v210 offset:21504
	ds_read_b128 v[216:219], v210 offset:22528
	ds_read_b128 v[224:227], v210 offset:23552
	global_load_lds_dwordx4 v[204:205], off
	s_add_i32 m0, s90, 0x2000
	s_add_u32 s90, s52, 0x100000
	v_lshl_add_u64 v[220:221], s[52:53], 0, v[178:179]
	s_addc_u32 s91, s53, 0
	s_add_i32 s92, s66, s31
	global_load_lds_dwordx4 v[220:221], off
	v_lshl_add_u64 v[228:229], s[90:91], 0, v[182:183]
	s_mov_b32 m0, s92
	v_lshl_add_u64 v[230:231], s[54:55], 0, v[180:181]
	global_load_lds_dwordx4 v[228:229], off
	v_lshl_add_u64 v[228:229], s[90:91], 0, v[178:179]
	s_add_i32 m0, s92, 0x2000
	s_nop 0
	global_load_lds_dwordx4 v[228:229], off
	v_lshl_add_u64 v[228:229], s[54:55], 0, v[184:185]
	s_mov_b32 m0, s56
	s_nop 0
	global_load_lds_dwordx4 v[228:229], off
	s_mov_b32 m0, s57
	s_nop 0
	global_load_lds_dwordx4 v[230:231], off
	s_waitcnt vmcnt(8)
	s_waitcnt lgkmcnt(0)
	s_setprio 1
	s_barrier
	v_mfma_f32_16x16x32_bf16 v[62:65], v[130:133], v[162:165], v[62:65]
	v_mfma_f32_16x16x32_bf16 v[58:61], v[138:141], v[162:165], v[58:61]
	v_mfma_f32_16x16x32_bf16 v[50:53], v[130:133], v[170:173], v[50:53]
	v_mfma_f32_16x16x32_bf16 v[42:45], v[138:141], v[170:173], v[42:45]
	v_mfma_f32_16x16x32_bf16 v[34:37], v[130:133], v[200:203], v[34:37]
	v_mfma_f32_16x16x32_bf16 v[26:29], v[138:141], v[200:203], v[26:29]
	v_mfma_f32_16x16x32_bf16 v[18:21], v[130:133], v[216:219], v[18:21]
	v_mfma_f32_16x16x32_bf16 v[10:13], v[138:141], v[216:219], v[10:13]
	v_mfma_f32_16x16x32_bf16 v[62:65], v[134:137], v[166:169], v[62:65]
	v_mfma_f32_16x16x32_bf16 v[58:61], v[142:145], v[166:169], v[58:61]
	v_mfma_f32_16x16x32_bf16 v[50:53], v[134:137], v[174:177], v[50:53]
	v_mfma_f32_16x16x32_bf16 v[42:45], v[142:145], v[174:177], v[42:45]
	v_mfma_f32_16x16x32_bf16 v[34:37], v[134:137], v[212:215], v[34:37]
	v_mfma_f32_16x16x32_bf16 v[26:29], v[142:145], v[212:215], v[26:29]
	v_mfma_f32_16x16x32_bf16 v[18:21], v[134:137], v[224:227], v[18:21]
	v_mfma_f32_16x16x32_bf16 v[10:13], v[142:145], v[224:227], v[10:13]
	v_mfma_f32_16x16x32_bf16 v[54:57], v[146:149], v[162:165], v[54:57]
	v_mfma_f32_16x16x32_bf16 v[46:49], v[154:157], v[162:165], v[46:49]
	v_mfma_f32_16x16x32_bf16 v[38:41], v[146:149], v[170:173], v[38:41]
	v_mfma_f32_16x16x32_bf16 v[30:33], v[154:157], v[170:173], v[30:33]
	v_mfma_f32_16x16x32_bf16 v[22:25], v[146:149], v[200:203], v[22:25]
	v_mfma_f32_16x16x32_bf16 v[14:17], v[154:157], v[200:203], v[14:17]
	v_mfma_f32_16x16x32_bf16 v[6:9], v[146:149], v[216:219], v[6:9]
	v_mfma_f32_16x16x32_bf16 v[2:5], v[154:157], v[216:219], v[2:5]
	v_mfma_f32_16x16x32_bf16 v[54:57], v[150:153], v[166:169], v[54:57]
	v_mfma_f32_16x16x32_bf16 v[46:49], v[158:161], v[166:169], v[46:49]
	v_mfma_f32_16x16x32_bf16 v[38:41], v[150:153], v[174:177], v[38:41]
	v_mfma_f32_16x16x32_bf16 v[30:33], v[158:161], v[174:177], v[30:33]
	v_mfma_f32_16x16x32_bf16 v[22:25], v[150:153], v[212:215], v[22:25]
	v_mfma_f32_16x16x32_bf16 v[14:17], v[158:161], v[212:215], v[14:17]
	v_mfma_f32_16x16x32_bf16 v[6:9], v[150:153], v[224:227], v[6:9]
	v_mfma_f32_16x16x32_bf16 v[2:5], v[158:161], v[224:227], v[2:5]
	s_barrier
	s_setprio 0
	s_add_i32 s90, 0, 0x18000
	s_add_i32 s91, 0, 0x1c000
	v_add_u32_e32 v142, s90, v189
	v_add_u32_e32 v158, s91, v189
	ds_read_b128 v[130:133], v142
	ds_read_b128 v[134:137], v142 offset:1024
	ds_read_b128 v[138:141], v142 offset:2048
	ds_read_b128 v[142:145], v142 offset:3072
	ds_read_b128 v[146:149], v158
	ds_read_b128 v[150:153], v158 offset:1024
	ds_read_b128 v[154:157], v158 offset:2048
	ds_read_b128 v[158:161], v158 offset:3072
	s_add_u32 s54, s54, 0x100000
	s_addc_u32 s55, s55, 0
	s_mov_b32 m0, s58
	v_lshl_add_u64 v[232:233], s[54:55], 0, v[184:185]
	ds_read_b128 v[162:165], v210 offset:32768
	ds_read_b128 v[166:169], v210 offset:33792
	ds_read_b128 v[170:173], v210 offset:34816
	ds_read_b128 v[174:177], v210 offset:35840
	ds_read_b128 v[200:203], v210 offset:36864
	ds_read_b128 v[212:215], v210 offset:37888
	ds_read_b128 v[216:219], v210 offset:38912
	ds_read_b128 v[224:227], v210 offset:39936
	global_load_lds_dwordx4 v[232:233], off
	v_lshl_add_u64 v[232:233], s[54:55], 0, v[180:181]
	s_mov_b32 m0, s59
	s_nop 0
	global_load_lds_dwordx4 v[232:233], off
	s_waitcnt vmcnt(8)
	s_waitcnt lgkmcnt(0)
	s_setprio 1
	s_barrier
	v_mfma_f32_16x16x32_bf16 v[126:129], v[130:133], v[162:165], v[126:129]
	v_mfma_f32_16x16x32_bf16 v[122:125], v[138:141], v[162:165], v[122:125]
	v_mfma_f32_16x16x32_bf16 v[110:113], v[130:133], v[170:173], v[110:113]
	v_mfma_f32_16x16x32_bf16 v[106:109], v[138:141], v[170:173], v[106:109]
	v_mfma_f32_16x16x32_bf16 v[94:97], v[130:133], v[200:203], v[94:97]
	v_mfma_f32_16x16x32_bf16 v[90:93], v[138:141], v[200:203], v[90:93]
	v_mfma_f32_16x16x32_bf16 v[78:81], v[130:133], v[216:219], v[78:81]
	v_mfma_f32_16x16x32_bf16 v[74:77], v[138:141], v[216:219], v[74:77]
	v_mfma_f32_16x16x32_bf16 v[126:129], v[134:137], v[166:169], v[126:129]
	v_mfma_f32_16x16x32_bf16 v[122:125], v[142:145], v[166:169], v[122:125]
	v_mfma_f32_16x16x32_bf16 v[110:113], v[134:137], v[174:177], v[110:113]
	v_mfma_f32_16x16x32_bf16 v[106:109], v[142:145], v[174:177], v[106:109]
	v_mfma_f32_16x16x32_bf16 v[94:97], v[134:137], v[212:215], v[94:97]
	v_mfma_f32_16x16x32_bf16 v[90:93], v[142:145], v[212:215], v[90:93]
	v_mfma_f32_16x16x32_bf16 v[78:81], v[134:137], v[224:227], v[78:81]
	v_mfma_f32_16x16x32_bf16 v[74:77], v[142:145], v[224:227], v[74:77]
	v_mfma_f32_16x16x32_bf16 v[118:121], v[146:149], v[162:165], v[118:121]
	v_mfma_f32_16x16x32_bf16 v[114:117], v[154:157], v[162:165], v[114:117]
	v_mfma_f32_16x16x32_bf16 v[102:105], v[146:149], v[170:173], v[102:105]
	v_mfma_f32_16x16x32_bf16 v[98:101], v[154:157], v[170:173], v[98:101]
	v_mfma_f32_16x16x32_bf16 v[86:89], v[146:149], v[200:203], v[86:89]
	v_mfma_f32_16x16x32_bf16 v[82:85], v[154:157], v[200:203], v[82:85]
	v_mfma_f32_16x16x32_bf16 v[70:73], v[146:149], v[216:219], v[70:73]
	v_mfma_f32_16x16x32_bf16 v[66:69], v[154:157], v[216:219], v[66:69]
	v_mfma_f32_16x16x32_bf16 v[118:121], v[150:153], v[166:169], v[118:121]
	v_mfma_f32_16x16x32_bf16 v[114:117], v[158:161], v[166:169], v[114:117]
	v_mfma_f32_16x16x32_bf16 v[102:105], v[150:153], v[174:177], v[102:105]
	v_mfma_f32_16x16x32_bf16 v[98:101], v[158:161], v[174:177], v[98:101]
	v_mfma_f32_16x16x32_bf16 v[86:89], v[150:153], v[212:215], v[86:89]
	v_mfma_f32_16x16x32_bf16 v[82:85], v[158:161], v[212:215], v[82:85]
	v_mfma_f32_16x16x32_bf16 v[70:73], v[150:153], v[224:227], v[70:73]
	v_mfma_f32_16x16x32_bf16 v[66:69], v[158:161], v[224:227], v[66:69]
	s_barrier
	s_setprio 0
	s_add_i32 s54, s90, s31
	v_lshl_add_u64 v[204:205], v[204:205], 0, s[8:9]
	s_mov_b32 m0, s54
	ds_read_b128 v[162:165], v210 offset:49152
	ds_read_b128 v[166:169], v210 offset:50176
	ds_read_b128 v[170:173], v210 offset:51200
	ds_read_b128 v[174:177], v210 offset:52224
	ds_read_b128 v[200:203], v210 offset:53248
	ds_read_b128 v[212:215], v210 offset:54272
	ds_read_b128 v[216:219], v210 offset:55296
	ds_read_b128 v[224:227], v210 offset:56320
	global_load_lds_dwordx4 v[204:205], off
	s_add_i32 m0, s54, 0x2000
	s_add_u32 s52, s52, 0x100080
	v_lshl_add_u64 v[204:205], v[220:221], 0, s[8:9]
	s_addc_u32 s53, s53, 0
	s_add_i32 s54, s91, s31
	global_load_lds_dwordx4 v[204:205], off
	v_lshl_add_u64 v[204:205], s[52:53], 0, v[182:183]
	s_mov_b32 m0, s54
	s_nop 0
	global_load_lds_dwordx4 v[204:205], off
	v_lshl_add_u64 v[204:205], s[52:53], 0, v[178:179]
	s_add_i32 m0, s54, 0x2000
	s_nop 0
	global_load_lds_dwordx4 v[204:205], off
	v_lshl_add_u64 v[204:205], v[228:229], 0, s[8:9]
	s_mov_b32 m0, s62
	s_nop 0
	global_load_lds_dwordx4 v[204:205], off
	v_lshl_add_u64 v[204:205], v[230:231], 0, s[8:9]
	s_mov_b32 m0, s63
	s_nop 0
	global_load_lds_dwordx4 v[204:205], off
	s_waitcnt vmcnt(8)
	s_waitcnt lgkmcnt(0)
	s_setprio 1
	s_barrier
	v_mfma_f32_16x16x32_bf16 v[62:65], v[130:133], v[162:165], v[62:65]
	v_mfma_f32_16x16x32_bf16 v[58:61], v[138:141], v[162:165], v[58:61]
	v_mfma_f32_16x16x32_bf16 v[50:53], v[130:133], v[170:173], v[50:53]
	v_mfma_f32_16x16x32_bf16 v[42:45], v[138:141], v[170:173], v[42:45]
	v_mfma_f32_16x16x32_bf16 v[34:37], v[130:133], v[200:203], v[34:37]
	v_mfma_f32_16x16x32_bf16 v[26:29], v[138:141], v[200:203], v[26:29]
	v_mfma_f32_16x16x32_bf16 v[18:21], v[130:133], v[216:219], v[18:21]
	v_mfma_f32_16x16x32_bf16 v[10:13], v[138:141], v[216:219], v[10:13]
	v_mfma_f32_16x16x32_bf16 v[62:65], v[134:137], v[166:169], v[62:65]
	v_mfma_f32_16x16x32_bf16 v[58:61], v[142:145], v[166:169], v[58:61]
	v_mfma_f32_16x16x32_bf16 v[50:53], v[134:137], v[174:177], v[50:53]
	v_mfma_f32_16x16x32_bf16 v[42:45], v[142:145], v[174:177], v[42:45]
	v_mfma_f32_16x16x32_bf16 v[34:37], v[134:137], v[212:215], v[34:37]
	v_mfma_f32_16x16x32_bf16 v[26:29], v[142:145], v[212:215], v[26:29]
	v_mfma_f32_16x16x32_bf16 v[18:21], v[134:137], v[224:227], v[18:21]
	v_mfma_f32_16x16x32_bf16 v[10:13], v[142:145], v[224:227], v[10:13]
	v_mfma_f32_16x16x32_bf16 v[54:57], v[146:149], v[162:165], v[54:57]
	v_mfma_f32_16x16x32_bf16 v[46:49], v[154:157], v[162:165], v[46:49]
	v_mfma_f32_16x16x32_bf16 v[38:41], v[146:149], v[170:173], v[38:41]
	v_mfma_f32_16x16x32_bf16 v[30:33], v[154:157], v[170:173], v[30:33]
	v_mfma_f32_16x16x32_bf16 v[22:25], v[146:149], v[200:203], v[22:25]
	v_mfma_f32_16x16x32_bf16 v[14:17], v[154:157], v[200:203], v[14:17]
	v_mfma_f32_16x16x32_bf16 v[6:9], v[146:149], v[216:219], v[6:9]
	v_mfma_f32_16x16x32_bf16 v[2:5], v[154:157], v[216:219], v[2:5]
	v_mfma_f32_16x16x32_bf16 v[54:57], v[150:153], v[166:169], v[54:57]
	v_mfma_f32_16x16x32_bf16 v[46:49], v[158:161], v[166:169], v[46:49]
	v_mfma_f32_16x16x32_bf16 v[38:41], v[150:153], v[174:177], v[38:41]
	v_mfma_f32_16x16x32_bf16 v[30:33], v[158:161], v[174:177], v[30:33]
	v_mfma_f32_16x16x32_bf16 v[22:25], v[150:153], v[212:215], v[22:25]
	v_mfma_f32_16x16x32_bf16 v[14:17], v[158:161], v[212:215], v[14:17]
	v_mfma_f32_16x16x32_bf16 v[6:9], v[150:153], v[224:227], v[6:9]
	v_mfma_f32_16x16x32_bf16 v[2:5], v[158:161], v[224:227], v[2:5]
	s_barrier
	s_setprio 0
	s_add_i32 s89, s89, 2
	s_add_u32 s50, s50, 0x100
	s_addc_u32 s51, s51, 0
	s_add_u32 s87, s87, 0x100
	s_addc_u32 s88, s88, 0
	s_cmp_gt_u32 s89, 61
	s_cbranch_scc0 .LBB0_224
	s_and_b64 vcc, exec, s[10:11]
	s_cbranch_vccz .LBB0_229
	s_barrier
	v_lshl_add_u32 v200, s0, 8, v1
	s_cmp_gt_i32 s84, 15
	s_mov_b64 s[50:51], -1
	s_cbranch_scc1 .LBB0_230

.LBB0_672:
	v_add_u32_e32 v142, s51, v220
	v_add_u32_e32 v158, s81, v220
	ds_read_b128 v[130:133], v142
	ds_read_b128 v[134:137], v142 offset:1024
	ds_read_b128 v[138:141], v142 offset:2048
	ds_read_b128 v[142:145], v142 offset:3072
	ds_read_b128 v[146:149], v158
	ds_read_b128 v[150:153], v158 offset:1024
	ds_read_b128 v[154:157], v158 offset:2048
	ds_read_b128 v[158:161], v158 offset:3072
	s_add_u32 s16, s0, 0xfff00080
	s_addc_u32 s17, s1, -1
	s_cmp_eq_u32 s26, 60
	s_cselect_b32 s19, s20, s17
	s_cselect_b32 s18, s21, s16
	s_cselect_b32 s17, s22, s25
	s_cselect_b32 s16, s23, s24
	v_lshl_add_u64 v[218:219], s[0:1], 0, v[194:195]
	s_add_i32 m0, s31, 0xc000
	ds_read_b128 v[162:165], v233
	ds_read_b128 v[166:169], v233 offset:1024
	ds_read_b128 v[170:173], v233 offset:2048
	ds_read_b128 v[174:177], v233 offset:3072
	ds_read_b128 v[202:205], v233 offset:4096
	ds_read_b128 v[206:209], v233 offset:5120
	ds_read_b128 v[210:213], v233 offset:6144
	ds_read_b128 v[214:217], v233 offset:7168
	global_load_lds_dwordx4 v[218:219], off
	v_lshl_add_u64 v[218:219], s[0:1], 0, v[196:197]
	s_add_i32 m0, s31, 0xe000
	s_nop 0
	global_load_lds_dwordx4 v[218:219], off
	s_waitcnt vmcnt(8)
	s_waitcnt lgkmcnt(0)
	s_setprio 1
	s_barrier
	v_mfma_f32_16x16x32_bf16 v[90:93], v[130:133], v[162:165], v[90:93]
	v_mfma_f32_16x16x32_bf16 v[58:61], v[138:141], v[162:165], v[58:61]
	v_mfma_f32_16x16x32_bf16 v[98:101], v[130:133], v[170:173], v[98:101]
	v_mfma_f32_16x16x32_bf16 v[66:69], v[138:141], v[170:173], v[66:69]
	v_mfma_f32_16x16x32_bf16 v[102:105], v[130:133], v[202:205], v[102:105]
	v_mfma_f32_16x16x32_bf16 v[70:73], v[138:141], v[202:205], v[70:73]
	v_mfma_f32_16x16x32_bf16 v[110:113], v[130:133], v[210:213], v[110:113]
	v_mfma_f32_16x16x32_bf16 v[78:81], v[138:141], v[210:213], v[78:81]
	v_mfma_f32_16x16x32_bf16 v[90:93], v[134:137], v[166:169], v[90:93]
	v_mfma_f32_16x16x32_bf16 v[58:61], v[142:145], v[166:169], v[58:61]
	v_mfma_f32_16x16x32_bf16 v[98:101], v[134:137], v[174:177], v[98:101]
	v_mfma_f32_16x16x32_bf16 v[66:69], v[142:145], v[174:177], v[66:69]
	v_mfma_f32_16x16x32_bf16 v[102:105], v[134:137], v[206:209], v[102:105]
	v_mfma_f32_16x16x32_bf16 v[70:73], v[142:145], v[206:209], v[70:73]
	v_mfma_f32_16x16x32_bf16 v[110:113], v[134:137], v[214:217], v[110:113]
	v_mfma_f32_16x16x32_bf16 v[78:81], v[142:145], v[214:217], v[78:81]
	v_mfma_f32_16x16x32_bf16 v[26:29], v[146:149], v[162:165], v[26:29]
	v_mfma_f32_16x16x32_bf16 v[2:5], v[154:157], v[162:165], v[2:5]
	v_mfma_f32_16x16x32_bf16 v[34:37], v[146:149], v[170:173], v[34:37]
	v_mfma_f32_16x16x32_bf16 v[6:9], v[154:157], v[170:173], v[6:9]
	v_mfma_f32_16x16x32_bf16 v[38:41], v[146:149], v[202:205], v[38:41]
	v_mfma_f32_16x16x32_bf16 v[10:13], v[154:157], v[202:205], v[10:13]
	v_mfma_f32_16x16x32_bf16 v[46:49], v[146:149], v[210:213], v[46:49]
	v_mfma_f32_16x16x32_bf16 v[14:17], v[154:157], v[210:213], v[14:17]
	v_mfma_f32_16x16x32_bf16 v[26:29], v[150:153], v[166:169], v[26:29]
	v_mfma_f32_16x16x32_bf16 v[2:5], v[158:161], v[166:169], v[2:5]
	v_mfma_f32_16x16x32_bf16 v[34:37], v[150:153], v[174:177], v[34:37]
	v_mfma_f32_16x16x32_bf16 v[6:9], v[158:161], v[174:177], v[6:9]
	v_mfma_f32_16x16x32_bf16 v[38:41], v[150:153], v[206:209], v[38:41]
	v_mfma_f32_16x16x32_bf16 v[10:13], v[158:161], v[206:209], v[10:13]
	v_mfma_f32_16x16x32_bf16 v[46:49], v[150:153], v[214:217], v[46:49]
	v_mfma_f32_16x16x32_bf16 v[14:17], v[158:161], v[214:217], v[14:17]
	s_barrier
	s_setprio 0
	s_add_i32 s27, s51, s15
	v_lshl_add_u64 v[218:219], s[16:17], 0, v[178:179]
	s_mov_b32 m0, s27
	ds_read_b128 v[162:165], v233 offset:16384
	ds_read_b128 v[166:169], v233 offset:17408
	ds_read_b128 v[170:173], v233 offset:18432
	ds_read_b128 v[174:177], v233 offset:19456
	ds_read_b128 v[202:205], v233 offset:20480
	ds_read_b128 v[206:209], v233 offset:21504
	ds_read_b128 v[210:213], v233 offset:22528
	ds_read_b128 v[214:217], v233 offset:23552
	global_load_lds_dwordx4 v[218:219], off
	s_add_i32 m0, s27, 0x2000
	s_add_u32 s62, s16, 0x100000
	v_lshl_add_u64 v[242:243], s[16:17], 0, v[180:181]
	s_addc_u32 s63, s17, 0
	s_add_i32 s27, s81, s15
	global_load_lds_dwordx4 v[242:243], off
	v_lshl_add_u64 v[244:245], s[62:63], 0, v[178:179]
	s_mov_b32 m0, s27
	v_lshl_add_u64 v[246:247], s[18:19], 0, v[180:181]
	global_load_lds_dwordx4 v[244:245], off
	v_lshl_add_u64 v[244:245], s[62:63], 0, v[180:181]
	s_add_i32 m0, s27, 0x2000
	s_nop 0
	global_load_lds_dwordx4 v[244:245], off
	v_lshl_add_u64 v[244:245], s[18:19], 0, v[178:179]
	s_mov_b32 m0, s31
	s_nop 0
	global_load_lds_dwordx4 v[244:245], off
	s_mov_b32 m0, s34
	s_nop 0
	global_load_lds_dwordx4 v[246:247], off
	s_waitcnt vmcnt(8)
	s_waitcnt lgkmcnt(0)
	s_setprio 1
	s_barrier
	v_mfma_f32_16x16x32_bf16 v[114:117], v[130:133], v[162:165], v[114:117]
	v_mfma_f32_16x16x32_bf16 v[82:85], v[138:141], v[162:165], v[82:85]
	v_mfma_f32_16x16x32_bf16 v[118:121], v[130:133], v[170:173], v[118:121]
	v_mfma_f32_16x16x32_bf16 v[86:89], v[138:141], v[170:173], v[86:89]
	v_mfma_f32_16x16x32_bf16 v[122:125], v[130:133], v[202:205], v[122:125]
	v_mfma_f32_16x16x32_bf16 v[94:97], v[138:141], v[202:205], v[94:97]
	v_mfma_f32_16x16x32_bf16 v[126:129], v[130:133], v[210:213], v[126:129]
	v_mfma_f32_16x16x32_bf16 v[106:109], v[138:141], v[210:213], v[106:109]
	v_mfma_f32_16x16x32_bf16 v[114:117], v[134:137], v[166:169], v[114:117]
	v_mfma_f32_16x16x32_bf16 v[82:85], v[142:145], v[166:169], v[82:85]
	v_mfma_f32_16x16x32_bf16 v[118:121], v[134:137], v[174:177], v[118:121]
	v_mfma_f32_16x16x32_bf16 v[86:89], v[142:145], v[174:177], v[86:89]
	v_mfma_f32_16x16x32_bf16 v[122:125], v[134:137], v[206:209], v[122:125]
	v_mfma_f32_16x16x32_bf16 v[94:97], v[142:145], v[206:209], v[94:97]
	v_mfma_f32_16x16x32_bf16 v[126:129], v[134:137], v[214:217], v[126:129]
	v_mfma_f32_16x16x32_bf16 v[106:109], v[142:145], v[214:217], v[106:109]
	v_mfma_f32_16x16x32_bf16 v[50:53], v[146:149], v[162:165], v[50:53]
	v_mfma_f32_16x16x32_bf16 v[18:21], v[154:157], v[162:165], v[18:21]
	v_mfma_f32_16x16x32_bf16 v[54:57], v[146:149], v[170:173], v[54:57]
	v_mfma_f32_16x16x32_bf16 v[22:25], v[154:157], v[170:173], v[22:25]
	v_mfma_f32_16x16x32_bf16 v[62:65], v[146:149], v[202:205], v[62:65]
	v_mfma_f32_16x16x32_bf16 v[30:33], v[154:157], v[202:205], v[30:33]
	v_mfma_f32_16x16x32_bf16 v[74:77], v[146:149], v[210:213], v[74:77]
	v_mfma_f32_16x16x32_bf16 v[42:45], v[154:157], v[210:213], v[42:45]
	v_mfma_f32_16x16x32_bf16 v[50:53], v[150:153], v[166:169], v[50:53]
	v_mfma_f32_16x16x32_bf16 v[18:21], v[158:161], v[166:169], v[18:21]
	v_mfma_f32_16x16x32_bf16 v[54:57], v[150:153], v[174:177], v[54:57]
	v_mfma_f32_16x16x32_bf16 v[22:25], v[158:161], v[174:177], v[22:25]
	v_mfma_f32_16x16x32_bf16 v[62:65], v[150:153], v[206:209], v[62:65]
	v_mfma_f32_16x16x32_bf16 v[30:33], v[158:161], v[206:209], v[30:33]
	v_mfma_f32_16x16x32_bf16 v[74:77], v[150:153], v[214:217], v[74:77]
	v_mfma_f32_16x16x32_bf16 v[42:45], v[158:161], v[214:217], v[42:45]
	s_barrier
	s_setprio 0
	s_add_i32 s27, 0, 0x18000
	s_add_i32 s59, 0, 0x1c000
	v_add_u32_e32 v142, s27, v220
	v_add_u32_e32 v158, s59, v220
	ds_read_b128 v[130:133], v142
	ds_read_b128 v[134:137], v142 offset:1024
	ds_read_b128 v[138:141], v142 offset:2048
	ds_read_b128 v[142:145], v142 offset:3072
	ds_read_b128 v[146:149], v158
	ds_read_b128 v[150:153], v158 offset:1024
	ds_read_b128 v[154:157], v158 offset:2048
	ds_read_b128 v[158:161], v158 offset:3072
	s_add_u32 s18, s18, 0x100000
	s_addc_u32 s19, s19, 0
	s_mov_b32 m0, s35
	v_lshl_add_u64 v[248:249], s[18:19], 0, v[178:179]
	ds_read_b128 v[162:165], v233 offset:32768
	ds_read_b128 v[166:169], v233 offset:33792
	ds_read_b128 v[170:173], v233 offset:34816
	ds_read_b128 v[174:177], v233 offset:35840
	ds_read_b128 v[202:205], v233 offset:36864
	ds_read_b128 v[206:209], v233 offset:37888
	ds_read_b128 v[210:213], v233 offset:38912
	ds_read_b128 v[214:217], v233 offset:39936
	global_load_lds_dwordx4 v[248:249], off
	v_lshl_add_u64 v[248:249], s[18:19], 0, v[180:181]
	s_mov_b32 m0, s86
	s_nop 0
	global_load_lds_dwordx4 v[248:249], off
	s_waitcnt vmcnt(8)
	s_waitcnt lgkmcnt(0)
	s_setprio 1
	s_barrier
	v_mfma_f32_16x16x32_bf16 v[90:93], v[130:133], v[162:165], v[90:93]
	v_mfma_f32_16x16x32_bf16 v[58:61], v[138:141], v[162:165], v[58:61]
	v_mfma_f32_16x16x32_bf16 v[98:101], v[130:133], v[170:173], v[98:101]
	v_mfma_f32_16x16x32_bf16 v[66:69], v[138:141], v[170:173], v[66:69]
	v_mfma_f32_16x16x32_bf16 v[102:105], v[130:133], v[202:205], v[102:105]
	v_mfma_f32_16x16x32_bf16 v[70:73], v[138:141], v[202:205], v[70:73]
	v_mfma_f32_16x16x32_bf16 v[110:113], v[130:133], v[210:213], v[110:113]
	v_mfma_f32_16x16x32_bf16 v[78:81], v[138:141], v[210:213], v[78:81]
	v_mfma_f32_16x16x32_bf16 v[90:93], v[134:137], v[166:169], v[90:93]
	v_mfma_f32_16x16x32_bf16 v[58:61], v[142:145], v[166:169], v[58:61]
	v_mfma_f32_16x16x32_bf16 v[98:101], v[134:137], v[174:177], v[98:101]
	v_mfma_f32_16x16x32_bf16 v[66:69], v[142:145], v[174:177], v[66:69]
	v_mfma_f32_16x16x32_bf16 v[102:105], v[134:137], v[206:209], v[102:105]
	v_mfma_f32_16x16x32_bf16 v[70:73], v[142:145], v[206:209], v[70:73]
	v_mfma_f32_16x16x32_bf16 v[110:113], v[134:137], v[214:217], v[110:113]
	v_mfma_f32_16x16x32_bf16 v[78:81], v[142:145], v[214:217], v[78:81]
	v_mfma_f32_16x16x32_bf16 v[26:29], v[146:149], v[162:165], v[26:29]
	v_mfma_f32_16x16x32_bf16 v[2:5], v[154:157], v[162:165], v[2:5]
	v_mfma_f32_16x16x32_bf16 v[34:37], v[146:149], v[170:173], v[34:37]
	v_mfma_f32_16x16x32_bf16 v[6:9], v[154:157], v[170:173], v[6:9]
	v_mfma_f32_16x16x32_bf16 v[38:41], v[146:149], v[202:205], v[38:41]
	v_mfma_f32_16x16x32_bf16 v[10:13], v[154:157], v[202:205], v[10:13]
	v_mfma_f32_16x16x32_bf16 v[46:49], v[146:149], v[210:213], v[46:49]
	v_mfma_f32_16x16x32_bf16 v[14:17], v[154:157], v[210:213], v[14:17]
	v_mfma_f32_16x16x32_bf16 v[26:29], v[150:153], v[166:169], v[26:29]
	v_mfma_f32_16x16x32_bf16 v[2:5], v[158:161], v[166:169], v[2:5]
	v_mfma_f32_16x16x32_bf16 v[34:37], v[150:153], v[174:177], v[34:37]
	v_mfma_f32_16x16x32_bf16 v[6:9], v[158:161], v[174:177], v[6:9]
	v_mfma_f32_16x16x32_bf16 v[38:41], v[150:153], v[206:209], v[38:41]
	v_mfma_f32_16x16x32_bf16 v[10:13], v[158:161], v[206:209], v[10:13]
	v_mfma_f32_16x16x32_bf16 v[46:49], v[150:153], v[214:217], v[46:49]
	v_mfma_f32_16x16x32_bf16 v[14:17], v[158:161], v[214:217], v[14:17]
	s_barrier
	s_setprio 0
	s_add_i32 s18, s27, s15
	v_lshl_add_u64 v[218:219], v[218:219], 0, s[44:45]
	s_mov_b32 m0, s18
	ds_read_b128 v[162:165], v233 offset:49152
	ds_read_b128 v[166:169], v233 offset:50176
	ds_read_b128 v[170:173], v233 offset:51200
	ds_read_b128 v[174:177], v233 offset:52224
	ds_read_b128 v[202:205], v233 offset:53248
	ds_read_b128 v[206:209], v233 offset:54272
	ds_read_b128 v[210:213], v233 offset:55296
	ds_read_b128 v[214:217], v233 offset:56320
	global_load_lds_dwordx4 v[218:219], off
	s_add_i32 m0, s18, 0x2000
	s_add_u32 s16, s16, 0x100080
	v_lshl_add_u64 v[218:219], v[242:243], 0, s[44:45]
	s_addc_u32 s17, s17, 0
	s_add_i32 s18, s59, s15
	global_load_lds_dwordx4 v[218:219], off
	v_lshl_add_u64 v[218:219], s[16:17], 0, v[178:179]
	s_mov_b32 m0, s18
	s_nop 0
	global_load_lds_dwordx4 v[218:219], off
	v_lshl_add_u64 v[218:219], s[16:17], 0, v[180:181]
	s_add_i32 m0, s18, 0x2000
	s_nop 0
	global_load_lds_dwordx4 v[218:219], off
	v_lshl_add_u64 v[218:219], v[244:245], 0, s[44:45]
	s_mov_b32 m0, s66
	s_nop 0
	global_load_lds_dwordx4 v[218:219], off
	v_lshl_add_u64 v[218:219], v[246:247], 0, s[44:45]
	s_mov_b32 m0, s67
	s_nop 0
	global_load_lds_dwordx4 v[218:219], off
	s_waitcnt vmcnt(8)
	s_waitcnt lgkmcnt(0)
	s_setprio 1
	s_barrier
	v_mfma_f32_16x16x32_bf16 v[114:117], v[130:133], v[162:165], v[114:117]
	v_mfma_f32_16x16x32_bf16 v[82:85], v[138:141], v[162:165], v[82:85]
	v_mfma_f32_16x16x32_bf16 v[118:121], v[130:133], v[170:173], v[118:121]
	v_mfma_f32_16x16x32_bf16 v[86:89], v[138:141], v[170:173], v[86:89]
	v_mfma_f32_16x16x32_bf16 v[122:125], v[130:133], v[202:205], v[122:125]
	v_mfma_f32_16x16x32_bf16 v[94:97], v[138:141], v[202:205], v[94:97]
	v_mfma_f32_16x16x32_bf16 v[126:129], v[130:133], v[210:213], v[126:129]
	v_mfma_f32_16x16x32_bf16 v[106:109], v[138:141], v[210:213], v[106:109]
	v_mfma_f32_16x16x32_bf16 v[114:117], v[134:137], v[166:169], v[114:117]
	v_mfma_f32_16x16x32_bf16 v[82:85], v[142:145], v[166:169], v[82:85]
	v_mfma_f32_16x16x32_bf16 v[118:121], v[134:137], v[174:177], v[118:121]
	v_mfma_f32_16x16x32_bf16 v[86:89], v[142:145], v[174:177], v[86:89]
	v_mfma_f32_16x16x32_bf16 v[122:125], v[134:137], v[206:209], v[122:125]
	v_mfma_f32_16x16x32_bf16 v[94:97], v[142:145], v[206:209], v[94:97]
	v_mfma_f32_16x16x32_bf16 v[126:129], v[134:137], v[214:217], v[126:129]
	v_mfma_f32_16x16x32_bf16 v[106:109], v[142:145], v[214:217], v[106:109]
	v_mfma_f32_16x16x32_bf16 v[50:53], v[146:149], v[162:165], v[50:53]
	v_mfma_f32_16x16x32_bf16 v[18:21], v[154:157], v[162:165], v[18:21]
	v_mfma_f32_16x16x32_bf16 v[54:57], v[146:149], v[170:173], v[54:57]
	v_mfma_f32_16x16x32_bf16 v[22:25], v[154:157], v[170:173], v[22:25]
	v_mfma_f32_16x16x32_bf16 v[62:65], v[146:149], v[202:205], v[62:65]
	v_mfma_f32_16x16x32_bf16 v[30:33], v[154:157], v[202:205], v[30:33]
	v_mfma_f32_16x16x32_bf16 v[74:77], v[146:149], v[210:213], v[74:77]
	v_mfma_f32_16x16x32_bf16 v[42:45], v[154:157], v[210:213], v[42:45]
	v_mfma_f32_16x16x32_bf16 v[50:53], v[150:153], v[166:169], v[50:53]
	v_mfma_f32_16x16x32_bf16 v[18:21], v[158:161], v[166:169], v[18:21]
	v_mfma_f32_16x16x32_bf16 v[54:57], v[150:153], v[174:177], v[54:57]
	v_mfma_f32_16x16x32_bf16 v[22:25], v[158:161], v[174:177], v[22:25]
	v_mfma_f32_16x16x32_bf16 v[62:65], v[150:153], v[206:209], v[62:65]
	v_mfma_f32_16x16x32_bf16 v[30:33], v[158:161], v[206:209], v[30:33]
	v_mfma_f32_16x16x32_bf16 v[74:77], v[150:153], v[214:217], v[74:77]
	v_mfma_f32_16x16x32_bf16 v[42:45], v[158:161], v[214:217], v[42:45]
	s_barrier
	s_setprio 0
	s_add_i32 s26, s26, 2
	s_add_u32 s0, s0, 0x100
	s_addc_u32 s1, s1, 0
	s_add_u32 s24, s24, 0x100
	s_addc_u32 s25, s25, 0
	s_cmp_gt_u32 s26, 61
	s_cbranch_scc0 .LBB0_672
	s_and_b64 vcc, exec, s[90:91]
	s_cbranch_vccz .LBB0_675
	s_barrier

.LBB0_788:
	ds_read_b128 v[156:159], v153
	ds_read_b128 v[160:163], v153 offset:1024
	ds_read_b128 v[164:167], v153 offset:2048
	ds_read_b128 v[168:171], v153 offset:3072
	ds_read_b128 v[172:175], v154
	ds_read_b128 v[176:179], v154 offset:1024
	ds_read_b128 v[180:183], v154 offset:2048
	ds_read_b128 v[184:187], v154 offset:3072
	s_add_u32 s36, s26, 0xfff00080
	s_addc_u32 s37, s27, -1
	s_cmp_eq_u32 s54, 60
	s_cselect_b32 s39, s19, s37
	s_cselect_b32 s38, s50, s36
	s_cselect_b32 s37, s17, s53
	s_cselect_b32 s36, s51, s52
	v_lshl_add_u64 v[148:149], s[26:27], 0, v[140:141]
	s_add_i32 m0, s25, 0xc000
	ds_read_b128 v[188:191], v155
	ds_read_b128 v[192:195], v155 offset:1024
	ds_read_b128 v[196:199], v155 offset:2048
	ds_read_b128 v[200:203], v155 offset:3072
	ds_read_b128 v[204:207], v155 offset:4096
	ds_read_b128 v[208:211], v155 offset:5120
	ds_read_b128 v[212:215], v155 offset:6144
	ds_read_b128 v[216:219], v155 offset:7168
	global_load_lds_dwordx4 v[148:149], off
	v_lshl_add_u64 v[148:149], s[26:27], 0, v[142:143]
	s_add_i32 m0, s25, 0xe000
	s_nop 0
	global_load_lds_dwordx4 v[148:149], off
	s_waitcnt vmcnt(8)
	s_waitcnt lgkmcnt(0)
	s_setprio 1
	s_barrier
	v_mfma_f32_16x16x32_bf16 v[126:129], v[156:159], v[188:191], v[126:129]
	v_mfma_f32_16x16x32_bf16 v[122:125], v[164:167], v[188:191], v[122:125]
	v_mfma_f32_16x16x32_bf16 v[118:121], v[156:159], v[196:199], v[118:121]
	v_mfma_f32_16x16x32_bf16 v[114:117], v[164:167], v[196:199], v[114:117]
	v_mfma_f32_16x16x32_bf16 v[94:97], v[156:159], v[204:207], v[94:97]
	v_mfma_f32_16x16x32_bf16 v[90:93], v[164:167], v[204:207], v[90:93]
	v_mfma_f32_16x16x32_bf16 v[86:89], v[156:159], v[212:215], v[86:89]
	v_mfma_f32_16x16x32_bf16 v[82:85], v[164:167], v[212:215], v[82:85]
	v_mfma_f32_16x16x32_bf16 v[126:129], v[160:163], v[192:195], v[126:129]
	v_mfma_f32_16x16x32_bf16 v[122:125], v[168:171], v[192:195], v[122:125]
	v_mfma_f32_16x16x32_bf16 v[118:121], v[160:163], v[200:203], v[118:121]
	v_mfma_f32_16x16x32_bf16 v[114:117], v[168:171], v[200:203], v[114:117]
	v_mfma_f32_16x16x32_bf16 v[94:97], v[160:163], v[208:211], v[94:97]
	v_mfma_f32_16x16x32_bf16 v[90:93], v[168:171], v[208:211], v[90:93]
	v_mfma_f32_16x16x32_bf16 v[86:89], v[160:163], v[216:219], v[86:89]
	v_mfma_f32_16x16x32_bf16 v[82:85], v[168:171], v[216:219], v[82:85]
	v_mfma_f32_16x16x32_bf16 v[110:113], v[172:175], v[188:191], v[110:113]
	v_mfma_f32_16x16x32_bf16 v[106:109], v[180:183], v[188:191], v[106:109]
	v_mfma_f32_16x16x32_bf16 v[102:105], v[172:175], v[196:199], v[102:105]
	v_mfma_f32_16x16x32_bf16 v[98:101], v[180:183], v[196:199], v[98:101]
	v_mfma_f32_16x16x32_bf16 v[78:81], v[172:175], v[204:207], v[78:81]
	v_mfma_f32_16x16x32_bf16 v[74:77], v[180:183], v[204:207], v[74:77]
	v_mfma_f32_16x16x32_bf16 v[70:73], v[172:175], v[212:215], v[70:73]
	v_mfma_f32_16x16x32_bf16 v[66:69], v[180:183], v[212:215], v[66:69]
	v_mfma_f32_16x16x32_bf16 v[110:113], v[176:179], v[192:195], v[110:113]
	v_mfma_f32_16x16x32_bf16 v[106:109], v[184:187], v[192:195], v[106:109]
	v_mfma_f32_16x16x32_bf16 v[102:105], v[176:179], v[200:203], v[102:105]
	v_mfma_f32_16x16x32_bf16 v[98:101], v[184:187], v[200:203], v[98:101]
	v_mfma_f32_16x16x32_bf16 v[78:81], v[176:179], v[208:211], v[78:81]
	v_mfma_f32_16x16x32_bf16 v[74:77], v[184:187], v[208:211], v[74:77]
	v_mfma_f32_16x16x32_bf16 v[70:73], v[176:179], v[216:219], v[70:73]
	v_mfma_f32_16x16x32_bf16 v[66:69], v[184:187], v[216:219], v[66:69]
	s_barrier
	s_setprio 0
	s_add_i32 s55, s44, s13
	v_lshl_add_u64 v[148:149], s[36:37], 0, v[134:135]
	s_mov_b32 m0, s55
	ds_read_b128 v[188:191], v155 offset:16384
	ds_read_b128 v[192:195], v155 offset:17408
	ds_read_b128 v[196:199], v155 offset:18432
	ds_read_b128 v[200:203], v155 offset:19456
	ds_read_b128 v[204:207], v155 offset:20480
	ds_read_b128 v[208:211], v155 offset:21504
	ds_read_b128 v[212:215], v155 offset:22528
	ds_read_b128 v[216:219], v155 offset:23552
	global_load_lds_dwordx4 v[148:149], off
	s_add_i32 m0, s55, 0x2000
	s_add_u32 s56, s36, 0x100000
	v_lshl_add_u64 v[220:221], s[36:37], 0, v[130:131]
	s_addc_u32 s57, s37, 0
	s_add_i32 s55, s45, s13
	global_load_lds_dwordx4 v[220:221], off
	v_lshl_add_u64 v[224:225], s[56:57], 0, v[134:135]
	s_mov_b32 m0, s55
	v_lshl_add_u64 v[226:227], s[38:39], 0, v[132:133]
	global_load_lds_dwordx4 v[224:225], off
	v_lshl_add_u64 v[224:225], s[56:57], 0, v[130:131]
	s_add_i32 m0, s55, 0x2000
	s_nop 0
	global_load_lds_dwordx4 v[224:225], off
	v_lshl_add_u64 v[224:225], s[38:39], 0, v[136:137]
	s_mov_b32 m0, s25
	s_nop 0
	global_load_lds_dwordx4 v[224:225], off
	s_mov_b32 m0, s31
	s_nop 0
	global_load_lds_dwordx4 v[226:227], off
	s_waitcnt vmcnt(8)
	s_waitcnt lgkmcnt(0)
	s_setprio 1
	s_barrier
	v_mfma_f32_16x16x32_bf16 v[62:65], v[156:159], v[188:191], v[62:65]
	v_mfma_f32_16x16x32_bf16 v[58:61], v[164:167], v[188:191], v[58:61]
	v_mfma_f32_16x16x32_bf16 v[54:57], v[156:159], v[196:199], v[54:57]
	v_mfma_f32_16x16x32_bf16 v[50:53], v[164:167], v[196:199], v[50:53]
	v_mfma_f32_16x16x32_bf16 v[30:33], v[156:159], v[204:207], v[30:33]
	v_mfma_f32_16x16x32_bf16 v[26:29], v[164:167], v[204:207], v[26:29]
	v_mfma_f32_16x16x32_bf16 v[22:25], v[156:159], v[212:215], v[22:25]
	v_mfma_f32_16x16x32_bf16 v[18:21], v[164:167], v[212:215], v[18:21]
	v_mfma_f32_16x16x32_bf16 v[62:65], v[160:163], v[192:195], v[62:65]
	v_mfma_f32_16x16x32_bf16 v[58:61], v[168:171], v[192:195], v[58:61]
	v_mfma_f32_16x16x32_bf16 v[54:57], v[160:163], v[200:203], v[54:57]
	v_mfma_f32_16x16x32_bf16 v[50:53], v[168:171], v[200:203], v[50:53]
	v_mfma_f32_16x16x32_bf16 v[30:33], v[160:163], v[208:211], v[30:33]
	v_mfma_f32_16x16x32_bf16 v[26:29], v[168:171], v[208:211], v[26:29]
	v_mfma_f32_16x16x32_bf16 v[22:25], v[160:163], v[216:219], v[22:25]
	v_mfma_f32_16x16x32_bf16 v[18:21], v[168:171], v[216:219], v[18:21]
	v_mfma_f32_16x16x32_bf16 v[46:49], v[172:175], v[188:191], v[46:49]
	v_mfma_f32_16x16x32_bf16 v[42:45], v[180:183], v[188:191], v[42:45]
	v_mfma_f32_16x16x32_bf16 v[38:41], v[172:175], v[196:199], v[38:41]
	v_mfma_f32_16x16x32_bf16 v[34:37], v[180:183], v[196:199], v[34:37]
	v_mfma_f32_16x16x32_bf16 v[14:17], v[172:175], v[204:207], v[14:17]
	v_mfma_f32_16x16x32_bf16 v[10:13], v[180:183], v[204:207], v[10:13]
	v_mfma_f32_16x16x32_bf16 v[6:9], v[172:175], v[212:215], v[6:9]
	v_mfma_f32_16x16x32_bf16 v[2:5], v[180:183], v[212:215], v[2:5]
	v_mfma_f32_16x16x32_bf16 v[46:49], v[176:179], v[192:195], v[46:49]
	v_mfma_f32_16x16x32_bf16 v[42:45], v[184:187], v[192:195], v[42:45]
	v_mfma_f32_16x16x32_bf16 v[38:41], v[176:179], v[200:203], v[38:41]
	v_mfma_f32_16x16x32_bf16 v[34:37], v[184:187], v[200:203], v[34:37]
	v_mfma_f32_16x16x32_bf16 v[14:17], v[176:179], v[208:211], v[14:17]
	v_mfma_f32_16x16x32_bf16 v[10:13], v[184:187], v[208:211], v[10:13]
	v_mfma_f32_16x16x32_bf16 v[6:9], v[176:179], v[216:219], v[6:9]
	v_mfma_f32_16x16x32_bf16 v[2:5], v[184:187], v[216:219], v[2:5]
	s_barrier
	s_setprio 0
	s_add_i32 s55, 0, 0x18000
	s_add_i32 s56, 0, 0x1c000
	v_add_u32_e32 v168, s55, v151
	v_add_u32_e32 v184, s56, v151
	ds_read_b128 v[156:159], v168
	ds_read_b128 v[160:163], v168 offset:1024
	ds_read_b128 v[164:167], v168 offset:2048
	ds_read_b128 v[168:171], v168 offset:3072
	ds_read_b128 v[172:175], v184
	ds_read_b128 v[176:179], v184 offset:1024
	ds_read_b128 v[180:183], v184 offset:2048
	ds_read_b128 v[184:187], v184 offset:3072
	s_add_u32 s38, s38, 0x100000
	s_addc_u32 s39, s39, 0
	s_mov_b32 m0, s34
	v_lshl_add_u64 v[228:229], s[38:39], 0, v[136:137]
	ds_read_b128 v[188:191], v155 offset:32768
	ds_read_b128 v[192:195], v155 offset:33792
	ds_read_b128 v[196:199], v155 offset:34816
	ds_read_b128 v[200:203], v155 offset:35840
	ds_read_b128 v[204:207], v155 offset:36864
	ds_read_b128 v[208:211], v155 offset:37888
	ds_read_b128 v[212:215], v155 offset:38912
	ds_read_b128 v[216:219], v155 offset:39936
	global_load_lds_dwordx4 v[228:229], off
	v_lshl_add_u64 v[228:229], s[38:39], 0, v[132:133]
	s_mov_b32 m0, s35
	s_nop 0
	global_load_lds_dwordx4 v[228:229], off
	s_waitcnt vmcnt(8)
	s_waitcnt lgkmcnt(0)
	s_setprio 1
	s_barrier
	v_mfma_f32_16x16x32_bf16 v[126:129], v[156:159], v[188:191], v[126:129]
	v_mfma_f32_16x16x32_bf16 v[122:125], v[164:167], v[188:191], v[122:125]
	v_mfma_f32_16x16x32_bf16 v[118:121], v[156:159], v[196:199], v[118:121]
	v_mfma_f32_16x16x32_bf16 v[114:117], v[164:167], v[196:199], v[114:117]
	v_mfma_f32_16x16x32_bf16 v[94:97], v[156:159], v[204:207], v[94:97]
	v_mfma_f32_16x16x32_bf16 v[90:93], v[164:167], v[204:207], v[90:93]
	v_mfma_f32_16x16x32_bf16 v[86:89], v[156:159], v[212:215], v[86:89]
	v_mfma_f32_16x16x32_bf16 v[82:85], v[164:167], v[212:215], v[82:85]
	v_mfma_f32_16x16x32_bf16 v[126:129], v[160:163], v[192:195], v[126:129]
	v_mfma_f32_16x16x32_bf16 v[122:125], v[168:171], v[192:195], v[122:125]
	v_mfma_f32_16x16x32_bf16 v[118:121], v[160:163], v[200:203], v[118:121]
	v_mfma_f32_16x16x32_bf16 v[114:117], v[168:171], v[200:203], v[114:117]
	v_mfma_f32_16x16x32_bf16 v[94:97], v[160:163], v[208:211], v[94:97]
	v_mfma_f32_16x16x32_bf16 v[90:93], v[168:171], v[208:211], v[90:93]
	v_mfma_f32_16x16x32_bf16 v[86:89], v[160:163], v[216:219], v[86:89]
	v_mfma_f32_16x16x32_bf16 v[82:85], v[168:171], v[216:219], v[82:85]
	v_mfma_f32_16x16x32_bf16 v[110:113], v[172:175], v[188:191], v[110:113]
	v_mfma_f32_16x16x32_bf16 v[106:109], v[180:183], v[188:191], v[106:109]
	v_mfma_f32_16x16x32_bf16 v[102:105], v[172:175], v[196:199], v[102:105]
	v_mfma_f32_16x16x32_bf16 v[98:101], v[180:183], v[196:199], v[98:101]
	v_mfma_f32_16x16x32_bf16 v[78:81], v[172:175], v[204:207], v[78:81]
	v_mfma_f32_16x16x32_bf16 v[74:77], v[180:183], v[204:207], v[74:77]
	v_mfma_f32_16x16x32_bf16 v[70:73], v[172:175], v[212:215], v[70:73]
	v_mfma_f32_16x16x32_bf16 v[66:69], v[180:183], v[212:215], v[66:69]
	v_mfma_f32_16x16x32_bf16 v[110:113], v[176:179], v[192:195], v[110:113]
	v_mfma_f32_16x16x32_bf16 v[106:109], v[184:187], v[192:195], v[106:109]
	v_mfma_f32_16x16x32_bf16 v[102:105], v[176:179], v[200:203], v[102:105]
	v_mfma_f32_16x16x32_bf16 v[98:101], v[184:187], v[200:203], v[98:101]
	v_mfma_f32_16x16x32_bf16 v[78:81], v[176:179], v[208:211], v[78:81]
	v_mfma_f32_16x16x32_bf16 v[74:77], v[184:187], v[208:211], v[74:77]
	v_mfma_f32_16x16x32_bf16 v[70:73], v[176:179], v[216:219], v[70:73]
	v_mfma_f32_16x16x32_bf16 v[66:69], v[184:187], v[216:219], v[66:69]
	s_barrier
	s_setprio 0
	s_add_i32 s38, s55, s13
	v_lshl_add_u64 v[148:149], v[148:149], 0, s[6:7]
	s_mov_b32 m0, s38
	ds_read_b128 v[188:191], v155 offset:49152
	ds_read_b128 v[192:195], v155 offset:50176
	ds_read_b128 v[196:199], v155 offset:51200
	ds_read_b128 v[200:203], v155 offset:52224
	ds_read_b128 v[204:207], v155 offset:53248
	ds_read_b128 v[208:211], v155 offset:54272
	ds_read_b128 v[212:215], v155 offset:55296
	ds_read_b128 v[216:219], v155 offset:56320
	global_load_lds_dwordx4 v[148:149], off
	s_add_i32 m0, s38, 0x2000
	s_add_u32 s36, s36, 0x100080
	v_lshl_add_u64 v[148:149], v[220:221], 0, s[6:7]
	s_addc_u32 s37, s37, 0
	s_add_i32 s38, s56, s13
	global_load_lds_dwordx4 v[148:149], off
	v_lshl_add_u64 v[148:149], s[36:37], 0, v[134:135]
	s_mov_b32 m0, s38
	s_nop 0
	global_load_lds_dwordx4 v[148:149], off
	v_lshl_add_u64 v[148:149], s[36:37], 0, v[130:131]
	s_add_i32 m0, s38, 0x2000
	s_nop 0
	global_load_lds_dwordx4 v[148:149], off
	v_lshl_add_u64 v[148:149], v[224:225], 0, s[6:7]
	s_mov_b32 m0, s41
	s_nop 0
	global_load_lds_dwordx4 v[148:149], off
	v_lshl_add_u64 v[148:149], v[226:227], 0, s[6:7]
	s_mov_b32 m0, s42
	s_nop 0
	global_load_lds_dwordx4 v[148:149], off
	s_waitcnt vmcnt(8)
	s_waitcnt lgkmcnt(0)
	s_setprio 1
	s_barrier
	v_mfma_f32_16x16x32_bf16 v[62:65], v[156:159], v[188:191], v[62:65]
	v_mfma_f32_16x16x32_bf16 v[58:61], v[164:167], v[188:191], v[58:61]
	v_mfma_f32_16x16x32_bf16 v[54:57], v[156:159], v[196:199], v[54:57]
	v_mfma_f32_16x16x32_bf16 v[50:53], v[164:167], v[196:199], v[50:53]
	v_mfma_f32_16x16x32_bf16 v[30:33], v[156:159], v[204:207], v[30:33]
	v_mfma_f32_16x16x32_bf16 v[26:29], v[164:167], v[204:207], v[26:29]
	v_mfma_f32_16x16x32_bf16 v[22:25], v[156:159], v[212:215], v[22:25]
	v_mfma_f32_16x16x32_bf16 v[18:21], v[164:167], v[212:215], v[18:21]
	v_mfma_f32_16x16x32_bf16 v[62:65], v[160:163], v[192:195], v[62:65]
	v_mfma_f32_16x16x32_bf16 v[58:61], v[168:171], v[192:195], v[58:61]
	v_mfma_f32_16x16x32_bf16 v[54:57], v[160:163], v[200:203], v[54:57]
	v_mfma_f32_16x16x32_bf16 v[50:53], v[168:171], v[200:203], v[50:53]
	v_mfma_f32_16x16x32_bf16 v[30:33], v[160:163], v[208:211], v[30:33]
	v_mfma_f32_16x16x32_bf16 v[26:29], v[168:171], v[208:211], v[26:29]
	v_mfma_f32_16x16x32_bf16 v[22:25], v[160:163], v[216:219], v[22:25]
	v_mfma_f32_16x16x32_bf16 v[18:21], v[168:171], v[216:219], v[18:21]
	v_mfma_f32_16x16x32_bf16 v[46:49], v[172:175], v[188:191], v[46:49]
	v_mfma_f32_16x16x32_bf16 v[42:45], v[180:183], v[188:191], v[42:45]
	v_mfma_f32_16x16x32_bf16 v[38:41], v[172:175], v[196:199], v[38:41]
	v_mfma_f32_16x16x32_bf16 v[34:37], v[180:183], v[196:199], v[34:37]
	v_mfma_f32_16x16x32_bf16 v[14:17], v[172:175], v[204:207], v[14:17]
	v_mfma_f32_16x16x32_bf16 v[10:13], v[180:183], v[204:207], v[10:13]
	v_mfma_f32_16x16x32_bf16 v[6:9], v[172:175], v[212:215], v[6:9]
	v_mfma_f32_16x16x32_bf16 v[2:5], v[180:183], v[212:215], v[2:5]
	v_mfma_f32_16x16x32_bf16 v[46:49], v[176:179], v[192:195], v[46:49]
	v_mfma_f32_16x16x32_bf16 v[42:45], v[184:187], v[192:195], v[42:45]
	v_mfma_f32_16x16x32_bf16 v[38:41], v[176:179], v[200:203], v[38:41]
	v_mfma_f32_16x16x32_bf16 v[34:37], v[184:187], v[200:203], v[34:37]
	v_mfma_f32_16x16x32_bf16 v[14:17], v[176:179], v[208:211], v[14:17]
	v_mfma_f32_16x16x32_bf16 v[10:13], v[184:187], v[208:211], v[10:13]
	v_mfma_f32_16x16x32_bf16 v[6:9], v[176:179], v[216:219], v[6:9]
	v_mfma_f32_16x16x32_bf16 v[2:5], v[184:187], v[216:219], v[2:5]
	s_barrier
	s_setprio 0
	s_add_i32 s54, s54, 2
	s_add_u32 s26, s26, 0x100
	s_addc_u32 s27, s27, 0
	s_add_u32 s52, s52, 0x100
	s_addc_u32 s53, s53, 0
	s_cmp_gt_u32 s54, 61
	s_cbranch_scc0 .LBB0_788
	s_and_b64 vcc, exec, s[8:9]
	s_cbranch_vccz .LBB0_791
	s_barrier

.LBB0_1040:
	ds_read_b128 v[130:133], v207
	ds_read_b128 v[134:137], v207 offset:1024
	ds_read_b128 v[138:141], v207 offset:2048
	ds_read_b128 v[142:145], v207 offset:3072
	ds_read_b128 v[146:149], v208
	ds_read_b128 v[172:175], v208 offset:1024
	ds_read_b128 v[176:179], v208 offset:2048
	ds_read_b128 v[210:213], v208 offset:3072
	s_add_u32 s10, s8, 0xffd50080
	s_addc_u32 s11, s9, -1
	s_cmpk_eq_i32 s16, 0xa8
	s_cselect_b32 s13, s25, s11
	s_cselect_b32 s12, s24, s10
	s_cselect_b32 s11, s41, s15
	s_cselect_b32 s10, s40, s14
	v_lshl_add_u64 v[180:181], s[8:9], 0, v[166:167]
	s_add_i32 m0, s48, 0xc000
	ds_read_b128 v[214:217], v202
	ds_read_b128 v[218:221], v202 offset:1024
	ds_read_b128 v[224:227], v202 offset:2048
	ds_read_b128 v[228:231], v202 offset:3072
	ds_read_b128 v[232:235], v202 offset:4096
	ds_read_b128 v[236:239], v202 offset:5120
	ds_read_b128 v[240:243], v202 offset:6144
	ds_read_b128 v[244:247], v202 offset:7168
	global_load_lds_dwordx4 v[180:181], off
	v_lshl_add_u64 v[180:181], s[8:9], 0, v[168:169]
	s_add_i32 m0, s48, 0xe000
	s_nop 0
	global_load_lds_dwordx4 v[180:181], off
	s_waitcnt vmcnt(8)
	s_waitcnt lgkmcnt(0)
	s_setprio 1
	s_barrier
	v_mfma_f32_16x16x32_bf16 v[90:93], v[130:133], v[214:217], v[90:93]
	v_mfma_f32_16x16x32_bf16 v[74:77], v[138:141], v[214:217], v[74:77]
	v_mfma_f32_16x16x32_bf16 v[46:49], v[130:133], v[224:227], v[46:49]
	v_mfma_f32_16x16x32_bf16 v[42:45], v[138:141], v[224:227], v[42:45]
	v_mfma_f32_16x16x32_bf16 v[126:129], v[130:133], v[232:235], v[126:129]
	v_mfma_f32_16x16x32_bf16 v[122:125], v[138:141], v[232:235], v[122:125]
	v_mfma_f32_16x16x32_bf16 v[110:113], v[130:133], v[240:243], v[110:113]
	v_mfma_f32_16x16x32_bf16 v[106:109], v[138:141], v[240:243], v[106:109]
	v_mfma_f32_16x16x32_bf16 v[90:93], v[134:137], v[218:221], v[90:93]
	v_mfma_f32_16x16x32_bf16 v[74:77], v[142:145], v[218:221], v[74:77]
	v_mfma_f32_16x16x32_bf16 v[46:49], v[134:137], v[228:231], v[46:49]
	v_mfma_f32_16x16x32_bf16 v[42:45], v[142:145], v[228:231], v[42:45]
	v_mfma_f32_16x16x32_bf16 v[126:129], v[134:137], v[236:239], v[126:129]
	v_mfma_f32_16x16x32_bf16 v[122:125], v[142:145], v[236:239], v[122:125]
	v_mfma_f32_16x16x32_bf16 v[110:113], v[134:137], v[244:247], v[110:113]
	v_mfma_f32_16x16x32_bf16 v[106:109], v[142:145], v[244:247], v[106:109]
	v_mfma_f32_16x16x32_bf16 v[70:73], v[146:149], v[214:217], v[70:73]
	v_mfma_f32_16x16x32_bf16 v[66:69], v[176:179], v[214:217], v[66:69]
	v_mfma_f32_16x16x32_bf16 v[34:37], v[146:149], v[224:227], v[34:37]
	v_mfma_f32_16x16x32_bf16 v[38:41], v[176:179], v[224:227], v[38:41]
	v_mfma_f32_16x16x32_bf16 v[118:121], v[146:149], v[232:235], v[118:121]
	v_mfma_f32_16x16x32_bf16 v[114:117], v[176:179], v[232:235], v[114:117]
	v_mfma_f32_16x16x32_bf16 v[102:105], v[146:149], v[240:243], v[102:105]
	v_mfma_f32_16x16x32_bf16 v[98:101], v[176:179], v[240:243], v[98:101]
	v_mfma_f32_16x16x32_bf16 v[70:73], v[172:175], v[218:221], v[70:73]
	v_mfma_f32_16x16x32_bf16 v[66:69], v[210:213], v[218:221], v[66:69]
	v_mfma_f32_16x16x32_bf16 v[34:37], v[172:175], v[228:231], v[34:37]
	v_mfma_f32_16x16x32_bf16 v[38:41], v[210:213], v[228:231], v[38:41]
	v_mfma_f32_16x16x32_bf16 v[118:121], v[172:175], v[236:239], v[118:121]
	v_mfma_f32_16x16x32_bf16 v[114:117], v[210:213], v[236:239], v[114:117]
	v_mfma_f32_16x16x32_bf16 v[102:105], v[172:175], v[244:247], v[102:105]
	v_mfma_f32_16x16x32_bf16 v[98:101], v[210:213], v[244:247], v[98:101]
	s_barrier
	s_setprio 0
	s_add_i32 s17, s57, s46
	v_lshl_add_u64 v[180:181], s[10:11], 0, v[150:151]
	s_mov_b32 m0, s17
	ds_read_b128 v[214:217], v202 offset:16384
	ds_read_b128 v[218:221], v202 offset:17408
	ds_read_b128 v[224:227], v202 offset:18432
	ds_read_b128 v[228:231], v202 offset:19456
	ds_read_b128 v[232:235], v202 offset:20480
	ds_read_b128 v[236:239], v202 offset:21504
	ds_read_b128 v[240:243], v202 offset:22528
	ds_read_b128 v[244:247], v202 offset:23552
	global_load_lds_dwordx4 v[180:181], off
	s_add_i32 m0, s17, 0x2000
	s_add_u32 s18, s10, 0x2b0000
	v_lshl_add_u64 v[248:249], s[10:11], 0, v[152:153]
	s_addc_u32 s19, s11, 0
	s_add_i32 s17, s58, s46
	global_load_lds_dwordx4 v[248:249], off
	v_lshl_add_u64 v[250:251], s[18:19], 0, v[150:151]
	s_mov_b32 m0, s17
	v_lshl_add_u64 v[252:253], s[12:13], 0, v[152:153]
	global_load_lds_dwordx4 v[250:251], off
	v_lshl_add_u64 v[250:251], s[18:19], 0, v[152:153]
	s_add_i32 m0, s17, 0x2000
	s_nop 0
	global_load_lds_dwordx4 v[250:251], off
	v_lshl_add_u64 v[250:251], s[12:13], 0, v[150:151]
	s_mov_b32 m0, s48
	s_nop 0
	global_load_lds_dwordx4 v[250:251], off
	s_mov_b32 m0, s49
	s_nop 0
	global_load_lds_dwordx4 v[252:253], off
	s_waitcnt vmcnt(8)
	s_waitcnt lgkmcnt(0)
	s_setprio 1
	s_barrier
	v_mfma_f32_16x16x32_bf16 v[94:97], v[130:133], v[214:217], v[94:97]
	v_mfma_f32_16x16x32_bf16 v[86:89], v[138:141], v[214:217], v[86:89]
	v_mfma_f32_16x16x32_bf16 v[82:85], v[130:133], v[224:227], v[82:85]
	v_mfma_f32_16x16x32_bf16 v[78:81], v[138:141], v[224:227], v[78:81]
	v_mfma_f32_16x16x32_bf16 v[30:33], v[130:133], v[232:235], v[30:33]
	v_mfma_f32_16x16x32_bf16 v[26:29], v[138:141], v[232:235], v[26:29]
	v_mfma_f32_16x16x32_bf16 v[22:25], v[130:133], v[240:243], v[22:25]
	v_mfma_f32_16x16x32_bf16 v[18:21], v[138:141], v[240:243], v[18:21]
	v_mfma_f32_16x16x32_bf16 v[94:97], v[134:137], v[218:221], v[94:97]
	v_mfma_f32_16x16x32_bf16 v[86:89], v[142:145], v[218:221], v[86:89]
	v_mfma_f32_16x16x32_bf16 v[82:85], v[134:137], v[228:231], v[82:85]
	v_mfma_f32_16x16x32_bf16 v[78:81], v[142:145], v[228:231], v[78:81]
	v_mfma_f32_16x16x32_bf16 v[30:33], v[134:137], v[236:239], v[30:33]
	v_mfma_f32_16x16x32_bf16 v[26:29], v[142:145], v[236:239], v[26:29]
	v_mfma_f32_16x16x32_bf16 v[22:25], v[134:137], v[244:247], v[22:25]
	v_mfma_f32_16x16x32_bf16 v[18:21], v[142:145], v[244:247], v[18:21]
	v_mfma_f32_16x16x32_bf16 v[62:65], v[146:149], v[214:217], v[62:65]
	v_mfma_f32_16x16x32_bf16 v[58:61], v[176:179], v[214:217], v[58:61]
	v_mfma_f32_16x16x32_bf16 v[54:57], v[146:149], v[224:227], v[54:57]
	v_mfma_f32_16x16x32_bf16 v[50:53], v[176:179], v[224:227], v[50:53]
	v_mfma_f32_16x16x32_bf16 v[14:17], v[146:149], v[232:235], v[14:17]
	v_mfma_f32_16x16x32_bf16 v[6:9], v[176:179], v[232:235], v[6:9]
	v_mfma_f32_16x16x32_bf16 v[10:13], v[146:149], v[240:243], v[10:13]
	v_mfma_f32_16x16x32_bf16 v[2:5], v[176:179], v[240:243], v[2:5]
	v_mfma_f32_16x16x32_bf16 v[62:65], v[172:175], v[218:221], v[62:65]
	v_mfma_f32_16x16x32_bf16 v[58:61], v[210:213], v[218:221], v[58:61]
	v_mfma_f32_16x16x32_bf16 v[54:57], v[172:175], v[228:231], v[54:57]
	v_mfma_f32_16x16x32_bf16 v[50:53], v[210:213], v[228:231], v[50:53]
	v_mfma_f32_16x16x32_bf16 v[14:17], v[172:175], v[236:239], v[14:17]
	v_mfma_f32_16x16x32_bf16 v[6:9], v[210:213], v[236:239], v[6:9]
	v_mfma_f32_16x16x32_bf16 v[10:13], v[172:175], v[244:247], v[10:13]
	v_mfma_f32_16x16x32_bf16 v[2:5], v[210:213], v[244:247], v[2:5]
	s_barrier
	s_setprio 0
	s_add_i32 s17, 0, 0x18000
	s_add_i32 s18, 0, 0x1c000
	v_add_u32_e32 v142, s17, v182
	v_add_u32_e32 v154, s18, v182
	ds_read_b128 v[130:133], v142
	ds_read_b128 v[134:137], v142 offset:1024
	ds_read_b128 v[138:141], v142 offset:2048
	ds_read_b128 v[142:145], v142 offset:3072
	ds_read_b128 v[146:149], v154
	ds_read_b128 v[172:175], v154 offset:1024
	ds_read_b128 v[176:179], v154 offset:2048
	ds_read_b128 v[210:213], v154 offset:3072
	s_add_u32 s12, s12, 0x2b0000
	s_addc_u32 s13, s13, 0
	s_mov_b32 m0, s50
	v_lshl_add_u64 v[188:189], s[12:13], 0, v[150:151]
	ds_read_b128 v[214:217], v202 offset:32768
	ds_read_b128 v[218:221], v202 offset:33792
	ds_read_b128 v[224:227], v202 offset:34816
	ds_read_b128 v[228:231], v202 offset:35840
	ds_read_b128 v[232:235], v202 offset:36864
	ds_read_b128 v[236:239], v202 offset:37888
	ds_read_b128 v[240:243], v202 offset:38912
	ds_read_b128 v[244:247], v202 offset:39936
	global_load_lds_dwordx4 v[188:189], off
	v_lshl_add_u64 v[188:189], s[12:13], 0, v[152:153]
	s_mov_b32 m0, s51
	s_nop 0
	global_load_lds_dwordx4 v[188:189], off
	s_waitcnt vmcnt(8)
	s_waitcnt lgkmcnt(0)
	s_setprio 1
	s_barrier
	v_mfma_f32_16x16x32_bf16 v[90:93], v[130:133], v[214:217], v[90:93]
	v_mfma_f32_16x16x32_bf16 v[74:77], v[138:141], v[214:217], v[74:77]
	v_mfma_f32_16x16x32_bf16 v[46:49], v[130:133], v[224:227], v[46:49]
	v_mfma_f32_16x16x32_bf16 v[42:45], v[138:141], v[224:227], v[42:45]
	v_mfma_f32_16x16x32_bf16 v[126:129], v[130:133], v[232:235], v[126:129]
	v_mfma_f32_16x16x32_bf16 v[122:125], v[138:141], v[232:235], v[122:125]
	v_mfma_f32_16x16x32_bf16 v[110:113], v[130:133], v[240:243], v[110:113]
	v_mfma_f32_16x16x32_bf16 v[106:109], v[138:141], v[240:243], v[106:109]
	v_mfma_f32_16x16x32_bf16 v[90:93], v[134:137], v[218:221], v[90:93]
	v_mfma_f32_16x16x32_bf16 v[74:77], v[142:145], v[218:221], v[74:77]
	v_mfma_f32_16x16x32_bf16 v[46:49], v[134:137], v[228:231], v[46:49]
	v_mfma_f32_16x16x32_bf16 v[42:45], v[142:145], v[228:231], v[42:45]
	v_mfma_f32_16x16x32_bf16 v[126:129], v[134:137], v[236:239], v[126:129]
	v_mfma_f32_16x16x32_bf16 v[122:125], v[142:145], v[236:239], v[122:125]
	v_mfma_f32_16x16x32_bf16 v[110:113], v[134:137], v[244:247], v[110:113]
	v_mfma_f32_16x16x32_bf16 v[106:109], v[142:145], v[244:247], v[106:109]
	v_mfma_f32_16x16x32_bf16 v[70:73], v[146:149], v[214:217], v[70:73]
	v_mfma_f32_16x16x32_bf16 v[66:69], v[176:179], v[214:217], v[66:69]
	v_mfma_f32_16x16x32_bf16 v[34:37], v[146:149], v[224:227], v[34:37]
	v_mfma_f32_16x16x32_bf16 v[38:41], v[176:179], v[224:227], v[38:41]
	v_mfma_f32_16x16x32_bf16 v[118:121], v[146:149], v[232:235], v[118:121]
	v_mfma_f32_16x16x32_bf16 v[114:117], v[176:179], v[232:235], v[114:117]
	v_mfma_f32_16x16x32_bf16 v[102:105], v[146:149], v[240:243], v[102:105]
	v_mfma_f32_16x16x32_bf16 v[98:101], v[176:179], v[240:243], v[98:101]
	v_mfma_f32_16x16x32_bf16 v[70:73], v[172:175], v[218:221], v[70:73]
	v_mfma_f32_16x16x32_bf16 v[66:69], v[210:213], v[218:221], v[66:69]
	v_mfma_f32_16x16x32_bf16 v[34:37], v[172:175], v[228:231], v[34:37]
	v_mfma_f32_16x16x32_bf16 v[38:41], v[210:213], v[228:231], v[38:41]
	v_mfma_f32_16x16x32_bf16 v[118:121], v[172:175], v[236:239], v[118:121]
	v_mfma_f32_16x16x32_bf16 v[114:117], v[210:213], v[236:239], v[114:117]
	v_mfma_f32_16x16x32_bf16 v[102:105], v[172:175], v[244:247], v[102:105]
	v_mfma_f32_16x16x32_bf16 v[98:101], v[210:213], v[244:247], v[98:101]
	s_barrier
	s_setprio 0
	s_add_i32 s12, s17, s46
	v_lshl_add_u64 v[180:181], v[180:181], 0, s[30:31]
	s_mov_b32 m0, s12
	ds_read_b128 v[214:217], v202 offset:49152
	ds_read_b128 v[218:221], v202 offset:50176
	ds_read_b128 v[224:227], v202 offset:51200
	ds_read_b128 v[228:231], v202 offset:52224
	ds_read_b128 v[232:235], v202 offset:53248
	ds_read_b128 v[236:239], v202 offset:54272
	ds_read_b128 v[240:243], v202 offset:55296
	ds_read_b128 v[244:247], v202 offset:56320
	global_load_lds_dwordx4 v[180:181], off
	s_add_i32 m0, s12, 0x2000
	s_add_u32 s10, s10, 0x2b0080
	v_lshl_add_u64 v[180:181], v[248:249], 0, s[30:31]
	s_addc_u32 s11, s11, 0
	s_add_i32 s12, s18, s46
	global_load_lds_dwordx4 v[180:181], off
	v_lshl_add_u64 v[180:181], s[10:11], 0, v[150:151]
	s_mov_b32 m0, s12
	s_nop 0
	global_load_lds_dwordx4 v[180:181], off
	v_lshl_add_u64 v[180:181], s[10:11], 0, v[152:153]
	s_add_i32 m0, s12, 0x2000
	s_nop 0
	global_load_lds_dwordx4 v[180:181], off
	v_lshl_add_u64 v[180:181], v[250:251], 0, s[30:31]
	s_mov_b32 m0, s52
	s_nop 0
	global_load_lds_dwordx4 v[180:181], off
	v_lshl_add_u64 v[180:181], v[252:253], 0, s[30:31]
	s_mov_b32 m0, s53
	s_nop 0
	global_load_lds_dwordx4 v[180:181], off
	s_waitcnt vmcnt(8)
	s_waitcnt lgkmcnt(0)
	s_setprio 1
	s_barrier
	v_mfma_f32_16x16x32_bf16 v[94:97], v[130:133], v[214:217], v[94:97]
	v_mfma_f32_16x16x32_bf16 v[86:89], v[138:141], v[214:217], v[86:89]
	v_mfma_f32_16x16x32_bf16 v[82:85], v[130:133], v[224:227], v[82:85]
	v_mfma_f32_16x16x32_bf16 v[78:81], v[138:141], v[224:227], v[78:81]
	v_mfma_f32_16x16x32_bf16 v[30:33], v[130:133], v[232:235], v[30:33]
	v_mfma_f32_16x16x32_bf16 v[26:29], v[138:141], v[232:235], v[26:29]
	v_mfma_f32_16x16x32_bf16 v[22:25], v[130:133], v[240:243], v[22:25]
	v_mfma_f32_16x16x32_bf16 v[18:21], v[138:141], v[240:243], v[18:21]
	v_mfma_f32_16x16x32_bf16 v[94:97], v[134:137], v[218:221], v[94:97]
	v_mfma_f32_16x16x32_bf16 v[86:89], v[142:145], v[218:221], v[86:89]
	v_mfma_f32_16x16x32_bf16 v[82:85], v[134:137], v[228:231], v[82:85]
	v_mfma_f32_16x16x32_bf16 v[78:81], v[142:145], v[228:231], v[78:81]
	v_mfma_f32_16x16x32_bf16 v[30:33], v[134:137], v[236:239], v[30:33]
	v_mfma_f32_16x16x32_bf16 v[26:29], v[142:145], v[236:239], v[26:29]
	v_mfma_f32_16x16x32_bf16 v[22:25], v[134:137], v[244:247], v[22:25]
	v_mfma_f32_16x16x32_bf16 v[18:21], v[142:145], v[244:247], v[18:21]
	v_mfma_f32_16x16x32_bf16 v[62:65], v[146:149], v[214:217], v[62:65]
	v_mfma_f32_16x16x32_bf16 v[58:61], v[176:179], v[214:217], v[58:61]
	v_mfma_f32_16x16x32_bf16 v[54:57], v[146:149], v[224:227], v[54:57]
	v_mfma_f32_16x16x32_bf16 v[50:53], v[176:179], v[224:227], v[50:53]
	v_mfma_f32_16x16x32_bf16 v[14:17], v[146:149], v[232:235], v[14:17]
	v_mfma_f32_16x16x32_bf16 v[6:9], v[176:179], v[232:235], v[6:9]
	v_mfma_f32_16x16x32_bf16 v[10:13], v[146:149], v[240:243], v[10:13]
	v_mfma_f32_16x16x32_bf16 v[2:5], v[176:179], v[240:243], v[2:5]
	v_mfma_f32_16x16x32_bf16 v[62:65], v[172:175], v[218:221], v[62:65]
	v_mfma_f32_16x16x32_bf16 v[58:61], v[210:213], v[218:221], v[58:61]
	v_mfma_f32_16x16x32_bf16 v[54:57], v[172:175], v[228:231], v[54:57]
	v_mfma_f32_16x16x32_bf16 v[50:53], v[210:213], v[228:231], v[50:53]
	v_mfma_f32_16x16x32_bf16 v[14:17], v[172:175], v[236:239], v[14:17]
	v_mfma_f32_16x16x32_bf16 v[6:9], v[210:213], v[236:239], v[6:9]
	v_mfma_f32_16x16x32_bf16 v[10:13], v[172:175], v[244:247], v[10:13]
	v_mfma_f32_16x16x32_bf16 v[2:5], v[210:213], v[244:247], v[2:5]
	s_barrier
	s_setprio 0
	s_add_i32 s16, s16, 2
	s_add_u32 s8, s8, 0x100
	s_addc_u32 s9, s9, 0
	s_add_u32 s14, s14, 0x100
	s_addc_u32 s15, s15, 0
	s_cmpk_gt_u32 s16, 0xa9
	s_cbranch_scc0 .LBB0_1040
	s_and_b64 vcc, exec, s[34:35]
	s_cbranch_vccz .LBB0_1043
	s_barrier
